# SB mask-free loop copy (v57) plus 128 bytes of unreachable padding so the merge K-loop keeps v54's code placement (mod 256)
# baseline (speedup 1.0000x reference)
; DI float bflo(unsigned w) { return __uint_as_float(w << 16); }
; DI float bfhi(unsigned w) { return __uint_as_float(w & 0xffff0000u); }
; DI void moba_combine_token(bf16_t* act, const unsigned* sel, const float* ml, int tok, int lane) {
;     const int hh = lane >> 3, ch = lane & 7;
;     const int b = tok >> 13, qpos = tok & (SEQ - 1);
;     bf16_t* rowp = act + (size_t)tok * PITCH;
;     const unsigned word = sel[(size_t)(b * 8 + hh) * SEQ + qpos];
;     const f32x4* mlp = (const f32x4*)(ml + ((size_t)tok * 8 + hh) * 8);
;     const f32x4 a = mlp[0], c = mlp[1];
;     const u32x4 v3 = *(const u32x4*)(rowp + C_KC + hh * 64 + ch * 8);
;     u32x4 vs[3];
; #pragma unroll
;     for (int s = 0; s < 3; ++s) vs[s] = *(const u32x4*)(rowp + C_KA + (s * 8 + hh) * 64 + ch * 8);
;     const u32x4 g = *(const u32x4*)(rowp + C_GB + hh * 64 + ch * 8);
;     const int ns = __popc(word);
;     const float m0 = ns > 0 ? a.x : NEG_INF, m1 = ns > 1 ? a.z : NEG_INF, m2 = ns > 2 ? c.x : NEG_INF, m3 = c.z;
;     const float M = fmaxf(fmaxf(m0, m1), fmaxf(m2, m3));
;     const float w0 = ns > 0 ? a.y * fast_exp2(m0 - M) : 0.f, w1 = ns > 1 ? a.w * fast_exp2(m1 - M) : 0.f, w2 = ns > 2 ? c.y * fast_exp2(m2 - M) : 0.f, w3 = c.w * fast_exp2(m3 - M);
;     const float inv = fast_rcp((w0 + w1) + (w2 + w3));
;     float acc[8];
;     acc[0] = w3 * bflo(v3.x); acc[1] = w3 * bfhi(v3.x); acc[2] = w3 * bflo(v3.y); acc[3] = w3 * bfhi(v3.y); acc[4] = w3 * bflo(v3.z); acc[5] = w3 * bfhi(v3.z); acc[6] = w3 * bflo(v3.w); acc[7] = w3 * bfhi(v3.w);
; #pragma unroll
;     for (int s = 0; s < 3; ++s) {
;         const float w = s == 0 ? w0 : (s == 1 ? w1 : w2);
;         const bool use = s < ns;
;         u32x4 v = vs[s]; if (!use) v = (u32x4){0u, 0u, 0u, 0u};
;         acc[0] += w * bflo(v.x); acc[1] += w * bfhi(v.x); acc[2] += w * bflo(v.y); acc[3] += w * bfhi(v.y); acc[4] += w * bflo(v.z); acc[5] += w * bfhi(v.z); acc[6] += w * bflo(v.w); acc[7] += w * bfhi(v.w);
; __global__ void __launch_bounds__(512, 2) hybrid_fwd(Params p) {
;     ...
;             for (int tok = gw; tok < T; tok += 2 * NGW) {
;                 moba_combine_token(act, (const unsigned*)(ws + WS_SEL), (const float*)(ws + WS_ML), tok, lane);
;                 if (tok + NGW < T) moba_combine_token(act, (const unsigned*)(ws + WS_SEL), (const float*)(ws + WS_ML), tok + NGW, lane);
.LBB0_583:
	s_and_b32 s14, s8, 0x1fff
	s_ashr_i32 s9, s8, 31
	s_mul_i32 s12, s8, 0x3200
	s_mul_hi_i32 s13, s8, 0x3200
	s_add_u32 s12, s10, s12
	s_addc_u32 s13, s11, s13
	s_ashr_i32 s15, s8, 10
	v_and_or_b32 v2, s15, -8, v13
	v_ashrrev_i32_e32 v3, 31, v2
	v_lshlrev_b64 v[2:3], 15, v[2:3]
	v_lshl_add_u64 v[2:3], s[6:7], 0, v[2:3]
	s_lshl_b32 s38, s14, 2
	v_lshl_add_u64 v[2:3], v[2:3], 0, s[38:39]
	global_load_dword v22, v[2:3], off
	s_lshl_b64 s[14:15], s[8:9], 8
	v_lshl_add_u64 v[2:3], v[10:11], 0, s[14:15]
	global_load_dwordx4 v[28:31], v[2:3], off offset:16
	global_load_dwordx4 v[18:21], v[2:3], off
	v_lshlrev_b32_e32 v0, 1, v12
	v_mov_b32_e32 v15, v1
	v_lshl_add_u64 v[2:3], s[12:13], 0, v[0:1]
	v_lshl_add_u64 v[2:3], v[2:3], 0, v[14:15]
	v_add_co_u32_e32 v4, vcc, s23, v2
	s_add_i32 s8, s8, s91
	s_nop 0
	v_addc_co_u32_e32 v5, vcc, 0, v3, vcc
	global_load_dwordx4 v[6:9], v[4:5], off offset:1024
	v_lshl_add_u64 v[4:5], s[12:13], 0, v[14:15]
	v_lshl_add_u64 v[4:5], v[4:5], 0, v[0:1]
	global_load_dwordx4 v[32:35], v[4:5], off offset:1024
	global_load_dwordx4 v[36:39], v[4:5], off offset:2048
	global_load_dwordx4 v[40:43], v[4:5], off offset:3072
	v_add_co_u32_e32 v16, vcc, s34, v2
	s_cmpk_gt_i32 s8, 0x7fff
	s_nop 0
	v_addc_co_u32_e32 v17, vcc, 0, v3, vcc
	global_load_dwordx4 v[2:5], v[16:17], off offset:3072
	s_waitcnt vmcnt(7)
	v_bcnt_u32_b32 v23, v22, 0
	v_cmp_lt_u32_e32 vcc, 2, v23
	v_cmp_eq_u32_e64 s[42:43], 0, v22
	v_cmp_lt_u32_e64 s[40:41], 1, v23
	s_waitcnt vmcnt(6)
	v_cndmask_b32_e32 v22, v235, v28, vcc
	v_max_f32_e32 v23, v22, v22
	v_max_f32_e32 v24, v30, v30
	s_waitcnt vmcnt(5)
	v_cndmask_b32_e64 v18, v18, v235, s[42:43]
	v_cndmask_b32_e64 v20, v235, v20, s[40:41]
	v_max_f32_e32 v23, v23, v24
	v_max3_f32 v23, v18, v20, v23
	v_sub_f32_e32 v18, v18, v23
	v_exp_f32_e32 v18, v18
	s_waitcnt vmcnt(3)
	v_cndmask_b32_e64 v28, v34, 0, s[42:43]
	v_cndmask_b32_e64 v44, v33, 0, s[42:43]
	v_mul_f32_e32 v18, v19, v18
	v_cndmask_b32_e64 v24, v18, 0, s[42:43]
	v_sub_f32_e32 v18, v20, v23
	v_exp_f32_e32 v18, v18
	s_waitcnt vmcnt(1)
	v_cndmask_b32_e32 v25, 0, v42, vcc
	v_cndmask_b32_e64 v27, 0, v38, s[40:41]
	v_cndmask_b32_e64 v36, 0, v36, s[40:41]
	v_mul_f32_e32 v18, v21, v18
	v_cndmask_b32_e64 v20, 0, v18, s[40:41]
	v_sub_f32_e32 v18, v22, v23
	v_exp_f32_e32 v18, v18
	v_and_b32_e32 v33, 0xffff0000, v6
	v_cndmask_b32_e64 v21, 0, v39, s[40:41]
	v_cndmask_b32_e32 v19, 0, v43, vcc
	v_mul_f32_e32 v18, v29, v18
	v_cndmask_b32_e32 v22, 0, v18, vcc
	v_sub_f32_e32 v18, v30, v23
	v_exp_f32_e32 v18, v18
	v_cndmask_b32_e64 v23, v35, 0, s[42:43]
	v_cndmask_b32_e64 v35, v32, 0, s[42:43]
	v_add_f32_e32 v32, v24, v20
	v_mul_f32_e32 v26, v31, v18
	v_fma_f32 v18, v31, v18, v22
	v_lshlrev_b32_e32 v34, 16, v35
	v_and_b32_e32 v35, 0xffff0000, v35
	v_add_f32_e32 v18, v32, v18
	v_lshlrev_b32_e32 v32, 16, v6
	v_pk_mul_f32 v[34:35], v[24:25], v[34:35] op_sel_hi:[0,1]
	v_cndmask_b32_e64 v30, 0, v37, s[40:41]
	v_cndmask_b32_e32 v37, 0, v40, vcc
	v_pk_fma_f32 v[32:33], v[26:27], v[32:33], v[34:35] op_sel_hi:[0,1,1]
	v_lshlrev_b32_e32 v34, 16, v36
	v_and_b32_e32 v35, 0xffff0000, v36
	v_pk_fma_f32 v[32:33], v[20:21], v[34:35], v[32:33] op_sel_hi:[0,1,1]
	v_lshlrev_b32_e32 v34, 16, v37
	v_and_b32_e32 v35, 0xffff0000, v37
	v_pk_fma_f32 v[32:33], v[22:23], v[34:35], v[32:33] op_sel_hi:[0,1,1]
	s_waitcnt vmcnt(0)
	v_lshlrev_b32_e32 v34, 16, v2
	v_and_b32_e32 v35, 0xffff0000, v2
	v_mul_f32_e32 v2, 0xbfb8aa3b, v34
	v_exp_f32_e32 v2, v2
	v_rcp_f32_e32 v18, v18
	v_lshlrev_b32_e32 v6, 16, v7
	v_and_b32_e32 v7, 0xffff0000, v7
	v_add_f32_e32 v2, 1.0, v2
	v_rcp_f32_e32 v36, v2
	v_mul_f32_e32 v2, 0xbfb8aa3b, v35
	v_exp_f32_e32 v2, v2
	v_pk_mul_f32 v[32:33], v[18:19], v[32:33] op_sel_hi:[0,1]
	v_cndmask_b32_e32 v29, 0, v41, vcc
	v_and_b32_e32 v31, 0xffff0000, v29
	v_add_f32_e32 v2, 1.0, v2
	v_rcp_f32_e32 v37, v2
	s_nop 0
	v_pk_mul_f32 v[34:35], v[36:37], v[34:35]
	s_nop 0
	v_pk_mul_f32 v[32:33], v[34:35], v[32:33]
	s_nop 0
	v_cvt_pk_bf16_f32 v2, v32, v33
	v_lshlrev_b32_e32 v32, 16, v44
	v_and_b32_e32 v33, 0xffff0000, v44
	v_pk_mul_f32 v[32:33], v[24:25], v[32:33] op_sel_hi:[0,1]
	v_pk_fma_f32 v[6:7], v[26:27], v[6:7], v[32:33] op_sel_hi:[0,1,1]
	v_lshlrev_b32_e32 v32, 16, v30
	v_and_b32_e32 v33, 0xffff0000, v30
	v_pk_fma_f32 v[6:7], v[20:21], v[32:33], v[6:7] op_sel_hi:[0,1,1]
	v_lshlrev_b32_e32 v30, 16, v29
	v_pk_fma_f32 v[6:7], v[22:23], v[30:31], v[6:7] op_sel_hi:[0,1,1]
	v_lshlrev_b32_e32 v30, 16, v3
	v_and_b32_e32 v31, 0xffff0000, v3
	v_mul_f32_e32 v3, 0xbfb8aa3b, v30
	v_exp_f32_e32 v3, v3
	v_pk_mul_f32 v[6:7], v[18:19], v[6:7] op_sel_hi:[0,1]
	v_add_f32_e32 v3, 1.0, v3
	v_rcp_f32_e32 v32, v3
	v_mul_f32_e32 v3, 0xbfb8aa3b, v31
	v_exp_f32_e32 v3, v3
	s_nop 0
	v_add_f32_e32 v3, 1.0, v3
	v_rcp_f32_e32 v33, v3
	s_nop 0
	v_pk_mul_f32 v[30:31], v[32:33], v[30:31]
	s_nop 0
	v_pk_mul_f32 v[6:7], v[30:31], v[6:7]
	v_lshlrev_b32_e32 v30, 16, v28
	v_and_b32_e32 v31, 0xffff0000, v28
	v_cvt_pk_bf16_f32 v3, v6, v7
	v_lshlrev_b32_e32 v6, 16, v8
	v_and_b32_e32 v7, 0xffff0000, v8
	v_pk_mul_f32 v[28:29], v[24:25], v[30:31] op_sel_hi:[0,1]
	v_pk_fma_f32 v[6:7], v[26:27], v[6:7], v[28:29] op_sel_hi:[0,1,1]
	v_lshlrev_b32_e32 v28, 16, v27
	v_and_b32_e32 v29, 0xffff0000, v27
	v_pk_fma_f32 v[6:7], v[20:21], v[28:29], v[6:7] op_sel_hi:[0,1,1]
	v_lshlrev_b32_e32 v28, 16, v25
	v_and_b32_e32 v29, 0xffff0000, v25
	v_pk_fma_f32 v[6:7], v[22:23], v[28:29], v[6:7] op_sel_hi:[0,1,1]
	v_lshlrev_b32_e32 v28, 16, v4
	v_and_b32_e32 v29, 0xffff0000, v4
	v_mul_f32_e32 v4, 0xbfb8aa3b, v28
	v_exp_f32_e32 v4, v4
	v_pk_mul_f32 v[6:7], v[18:19], v[6:7] op_sel_hi:[0,1]
	v_lshlrev_b32_e32 v8, 16, v23
	v_add_f32_e32 v4, 1.0, v4
	v_rcp_f32_e32 v30, v4
	v_mul_f32_e32 v4, 0xbfb8aa3b, v29
	v_exp_f32_e32 v4, v4
	s_nop 0
	v_add_f32_e32 v4, 1.0, v4
	v_rcp_f32_e32 v31, v4
	s_nop 0
	v_pk_mul_f32 v[28:29], v[30:31], v[28:29]
	s_nop 0
	v_pk_mul_f32 v[6:7], v[28:29], v[6:7]
	s_nop 0
	v_cvt_pk_bf16_f32 v4, v6, v7
	v_lshlrev_b32_e32 v6, 16, v9
	v_and_b32_e32 v7, 0xffff0000, v9
	v_and_b32_e32 v9, 0xffff0000, v23
	v_pk_mul_f32 v[8:9], v[24:25], v[8:9] op_sel_hi:[0,1]
	v_pk_fma_f32 v[6:7], v[26:27], v[6:7], v[8:9] op_sel_hi:[0,1,1]
	v_lshlrev_b32_e32 v8, 16, v21
	v_and_b32_e32 v9, 0xffff0000, v21
	v_pk_fma_f32 v[6:7], v[20:21], v[8:9], v[6:7] op_sel_hi:[0,1,1]
	v_lshlrev_b32_e32 v8, 16, v19
	v_and_b32_e32 v9, 0xffff0000, v19
	v_pk_fma_f32 v[6:7], v[22:23], v[8:9], v[6:7] op_sel_hi:[0,1,1]
	v_lshlrev_b32_e32 v8, 16, v5
	v_and_b32_e32 v9, 0xffff0000, v5
	v_mul_f32_e32 v5, 0xbfb8aa3b, v8
	v_exp_f32_e32 v5, v5
	v_pk_mul_f32 v[6:7], v[18:19], v[6:7] op_sel_hi:[0,1]
	v_add_f32_e32 v5, 1.0, v5
	v_rcp_f32_e32 v20, v5
	v_mul_f32_e32 v5, 0xbfb8aa3b, v9
	v_exp_f32_e32 v5, v5
	s_nop 0
	v_add_f32_e32 v5, 1.0, v5
	v_rcp_f32_e32 v21, v5
	s_nop 0
	v_pk_mul_f32 v[8:9], v[20:21], v[8:9]
	s_nop 0
	v_pk_mul_f32 v[6:7], v[8:9], v[6:7]
	s_nop 0
	v_cvt_pk_bf16_f32 v5, v6, v7
	global_store_dwordx4 v[16:17], v[2:5], off
	s_cbranch_scc1 .LBB0_582
; DI float bflo(unsigned w) { return __uint_as_float(w << 16); }
; DI float bfhi(unsigned w) { return __uint_as_float(w & 0xffff0000u); }
; DI void moba_combine_token(bf16_t* act, const unsigned* sel, const float* ml, int tok, int lane) {
;     const int hh = lane >> 3, ch = lane & 7;
;     const int b = tok >> 13, qpos = tok & (SEQ - 1);
;     bf16_t* rowp = act + (size_t)tok * PITCH;
;     const unsigned word = sel[(size_t)(b * 8 + hh) * SEQ + qpos];
;     const f32x4* mlp = (const f32x4*)(ml + ((size_t)tok * 8 + hh) * 8);
;     const f32x4 a = mlp[0], c = mlp[1];
;     const u32x4 v3 = *(const u32x4*)(rowp + C_KC + hh * 64 + ch * 8);
;     u32x4 vs[3];
; #pragma unroll
;     for (int s = 0; s < 3; ++s) vs[s] = *(const u32x4*)(rowp + C_KA + (s * 8 + hh) * 64 + ch * 8);
;     const u32x4 g = *(const u32x4*)(rowp + C_GB + hh * 64 + ch * 8);
;     const int ns = __popc(word);
;     const float m0 = ns > 0 ? a.x : NEG_INF, m1 = ns > 1 ? a.z : NEG_INF, m2 = ns > 2 ? c.x : NEG_INF, m3 = c.z;
;     const float M = fmaxf(fmaxf(m0, m1), fmaxf(m2, m3));
;     const float w0 = ns > 0 ? a.y * fast_exp2(m0 - M) : 0.f, w1 = ns > 1 ? a.w * fast_exp2(m1 - M) : 0.f, w2 = ns > 2 ? c.y * fast_exp2(m2 - M) : 0.f, w3 = c.w * fast_exp2(m3 - M);
;     const float inv = fast_rcp((w0 + w1) + (w2 + w3));
;     float acc[8];
;     acc[0] = w3 * bflo(v3.x); acc[1] = w3 * bfhi(v3.x); acc[2] = w3 * bflo(v3.y); acc[3] = w3 * bfhi(v3.y); acc[4] = w3 * bflo(v3.z); acc[5] = w3 * bfhi(v3.z); acc[6] = w3 * bflo(v3.w); acc[7] = w3 * bfhi(v3.w);
; #pragma unroll
;     for (int s = 0; s < 3; ++s) {
;         const float w = s == 0 ? w0 : (s == 1 ? w1 : w2);
;         const bool use = s < ns;
;         u32x4 v = vs[s]; if (!use) v = (u32x4){0u, 0u, 0u, 0u};
;         acc[0] += w * bflo(v.x); acc[1] += w * bfhi(v.x); acc[2] += w * bflo(v.y); acc[3] += w * bfhi(v.y); acc[4] += w * bflo(v.z); acc[5] += w * bfhi(v.z); acc[6] += w * bflo(v.w); acc[7] += w * bfhi(v.w);
;     }
;     u32x4 y;
;     y.x = cvtpk(acc[0] * inv * silu_(bflo(g.x)), acc[1] * inv * silu_(bfhi(g.x))); y.y = cvtpk(acc[2] * inv * silu_(bflo(g.y)), acc[3] * inv * silu_(bfhi(g.y)));
;     y.z = cvtpk(acc[4] * inv * silu_(bflo(g.z)), acc[5] * inv * silu_(bfhi(g.z))); y.w = cvtpk(acc[6] * inv * silu_(bflo(g.w)), acc[7] * inv * silu_(bfhi(g.w)));
;     *(u32x4*)(rowp + C_QB + hh * 64 + ch * 8) = y;
	s_and_b32 s14, s8, 0x1fff
	s_ashr_i32 s9, s8, 31
	s_mul_i32 s12, s8, 0x3200
	s_mul_hi_i32 s13, s8, 0x3200
	s_add_u32 s12, s10, s12
	s_addc_u32 s13, s11, s13
	s_ashr_i32 s15, s8, 10
	v_and_or_b32 v2, s15, -8, v13
	v_ashrrev_i32_e32 v3, 31, v2
	v_lshlrev_b64 v[2:3], 15, v[2:3]
	v_lshl_add_u64 v[2:3], s[6:7], 0, v[2:3]
	s_lshl_b32 s38, s14, 2
	v_lshl_add_u64 v[2:3], v[2:3], 0, s[38:39]
	global_load_dword v22, v[2:3], off
	s_lshl_b64 s[14:15], s[8:9], 8
	v_lshl_add_u64 v[2:3], v[10:11], 0, s[14:15]
	global_load_dwordx4 v[26:29], v[2:3], off offset:16
	global_load_dwordx4 v[18:21], v[2:3], off
	v_lshl_add_u64 v[2:3], s[12:13], 0, v[0:1]
	v_lshl_add_u64 v[2:3], v[2:3], 0, v[14:15]
	v_add_co_u32_e32 v4, vcc, s23, v2
	s_waitcnt vmcnt(2)
	v_cmp_eq_u32_e64 s[42:43], 0, v22
	v_addc_co_u32_e32 v5, vcc, 0, v3, vcc
	global_load_dwordx4 v[6:9], v[4:5], off offset:1024
	v_lshl_add_u64 v[4:5], s[12:13], 0, v[14:15]
	v_lshl_add_u64 v[4:5], v[4:5], 0, v[0:1]
	global_load_dwordx4 v[30:33], v[4:5], off offset:1024
	global_load_dwordx4 v[34:37], v[4:5], off offset:2048
	global_load_dwordx4 v[38:41], v[4:5], off offset:3072
	v_add_co_u32_e32 v16, vcc, s34, v2
	v_bcnt_u32_b32 v0, v22, 0
	s_nop 0
	v_addc_co_u32_e32 v17, vcc, 0, v3, vcc
	global_load_dwordx4 v[2:5], v[16:17], off offset:3072
	v_cmp_lt_u32_e32 vcc, 2, v0
	v_cmp_lt_u32_e64 s[40:41], 1, v0
	s_waitcnt vmcnt(5)
	v_cndmask_b32_e64 v15, v18, v235, s[42:43]
	v_cndmask_b32_e32 v0, v235, v26, vcc
	v_cndmask_b32_e64 v18, v235, v20, s[40:41]
	v_max_f32_e32 v20, v0, v0
	v_max_f32_e32 v22, v28, v28
	v_max_f32_e32 v20, v20, v22
	v_max3_f32 v23, v15, v18, v20
	v_sub_f32_e32 v15, v15, v23
	v_exp_f32_e32 v15, v15
	v_sub_f32_e32 v0, v0, v23
	v_exp_f32_e32 v0, v0
	v_mul_f32_e32 v15, v19, v15
	v_cndmask_b32_e64 v22, v15, 0, s[42:43]
	v_sub_f32_e32 v15, v18, v23
	v_exp_f32_e32 v15, v15
	v_mul_f32_e32 v0, v27, v0
	v_cndmask_b32_e32 v20, 0, v0, vcc
	v_sub_f32_e32 v0, v28, v23
	v_exp_f32_e32 v0, v0
	v_mul_f32_e32 v15, v21, v15
	v_cndmask_b32_e64 v18, 0, v15, s[40:41]
	v_mul_f32_e32 v24, v29, v0
	v_fma_f32 v0, v29, v0, v20
	s_waitcnt vmcnt(3)
	v_cndmask_b32_e64 v21, v33, 0, s[42:43]
	v_cndmask_b32_e64 v33, v30, 0, s[42:43]
	v_cndmask_b32_e64 v26, v32, 0, s[42:43]
	s_waitcnt vmcnt(1)
	v_cndmask_b32_e32 v23, 0, v40, vcc
	v_add_f32_e32 v30, v22, v18
	v_lshlrev_b32_e32 v32, 16, v33
	v_and_b32_e32 v33, 0xffff0000, v33
	v_cndmask_b32_e64 v42, v31, 0, s[42:43]
	v_cndmask_b32_e64 v25, 0, v36, s[40:41]
	v_cndmask_b32_e64 v34, 0, v34, s[40:41]
	v_add_f32_e32 v0, v30, v0
	v_lshlrev_b32_e32 v30, 16, v6
	v_and_b32_e32 v31, 0xffff0000, v6
	v_pk_mul_f32 v[32:33], v[22:23], v[32:33] op_sel_hi:[0,1]
	v_cndmask_b32_e64 v19, 0, v37, s[40:41]
	v_cndmask_b32_e64 v28, 0, v35, s[40:41]
	v_cndmask_b32_e32 v35, 0, v38, vcc
	v_pk_fma_f32 v[30:31], v[24:25], v[30:31], v[32:33] op_sel_hi:[0,1,1]
	v_lshlrev_b32_e32 v32, 16, v34
	v_and_b32_e32 v33, 0xffff0000, v34
	v_pk_fma_f32 v[30:31], v[18:19], v[32:33], v[30:31] op_sel_hi:[0,1,1]
	v_lshlrev_b32_e32 v32, 16, v35
	v_and_b32_e32 v33, 0xffff0000, v35
	v_pk_fma_f32 v[30:31], v[20:21], v[32:33], v[30:31] op_sel_hi:[0,1,1]
	s_waitcnt vmcnt(0)
	v_lshlrev_b32_e32 v32, 16, v2
	v_and_b32_e32 v33, 0xffff0000, v2
	v_mul_f32_e32 v2, 0xbfb8aa3b, v32
	v_exp_f32_e32 v2, v2
	v_rcp_f32_e32 v0, v0
	v_lshlrev_b32_e32 v6, 16, v7
	v_and_b32_e32 v7, 0xffff0000, v7
	v_add_f32_e32 v2, 1.0, v2
	v_rcp_f32_e32 v34, v2
	v_mul_f32_e32 v2, 0xbfb8aa3b, v33
	v_exp_f32_e32 v2, v2
	v_pk_mul_f32 v[30:31], v[0:1], v[30:31] op_sel_hi:[0,1]
	v_cndmask_b32_e32 v27, 0, v39, vcc
	v_and_b32_e32 v29, 0xffff0000, v27
	v_add_f32_e32 v2, 1.0, v2
	v_rcp_f32_e32 v35, v2
	v_cndmask_b32_e32 v15, 0, v41, vcc
	v_pk_mul_f32 v[32:33], v[34:35], v[32:33]
	s_nop 0
	v_pk_mul_f32 v[30:31], v[32:33], v[30:31]
	s_nop 0
	v_cvt_pk_bf16_f32 v2, v30, v31
	v_lshlrev_b32_e32 v30, 16, v42
	v_and_b32_e32 v31, 0xffff0000, v42
	v_pk_mul_f32 v[30:31], v[22:23], v[30:31] op_sel_hi:[0,1]
	v_pk_fma_f32 v[6:7], v[24:25], v[6:7], v[30:31] op_sel_hi:[0,1,1]
	v_lshlrev_b32_e32 v30, 16, v28
	v_and_b32_e32 v31, 0xffff0000, v28
	v_pk_fma_f32 v[6:7], v[18:19], v[30:31], v[6:7] op_sel_hi:[0,1,1]
	v_lshlrev_b32_e32 v28, 16, v27
	v_pk_fma_f32 v[6:7], v[20:21], v[28:29], v[6:7] op_sel_hi:[0,1,1]
	v_lshlrev_b32_e32 v28, 16, v3
	v_and_b32_e32 v29, 0xffff0000, v3
	v_mul_f32_e32 v3, 0xbfb8aa3b, v28
	v_exp_f32_e32 v3, v3
	v_pk_mul_f32 v[6:7], v[0:1], v[6:7] op_sel_hi:[0,1]
	v_add_f32_e32 v3, 1.0, v3
	v_rcp_f32_e32 v30, v3
	v_mul_f32_e32 v3, 0xbfb8aa3b, v29
	v_exp_f32_e32 v3, v3
	s_nop 0
	v_add_f32_e32 v3, 1.0, v3
	v_rcp_f32_e32 v31, v3
	s_nop 0
	v_pk_mul_f32 v[28:29], v[30:31], v[28:29]
	s_nop 0
	v_pk_mul_f32 v[6:7], v[28:29], v[6:7]
	v_lshlrev_b32_e32 v28, 16, v26
	v_and_b32_e32 v29, 0xffff0000, v26
	v_cvt_pk_bf16_f32 v3, v6, v7
	v_lshlrev_b32_e32 v6, 16, v8
	v_and_b32_e32 v7, 0xffff0000, v8
	v_pk_mul_f32 v[26:27], v[22:23], v[28:29] op_sel_hi:[0,1]
	v_pk_fma_f32 v[6:7], v[24:25], v[6:7], v[26:27] op_sel_hi:[0,1,1]
	v_lshlrev_b32_e32 v26, 16, v25
	v_and_b32_e32 v27, 0xffff0000, v25
	v_pk_fma_f32 v[6:7], v[18:19], v[26:27], v[6:7] op_sel_hi:[0,1,1]
	v_lshlrev_b32_e32 v26, 16, v23
	v_and_b32_e32 v27, 0xffff0000, v23
	v_pk_fma_f32 v[6:7], v[20:21], v[26:27], v[6:7] op_sel_hi:[0,1,1]
	v_lshlrev_b32_e32 v26, 16, v4
	v_and_b32_e32 v27, 0xffff0000, v4
	v_mul_f32_e32 v4, 0xbfb8aa3b, v26
	v_exp_f32_e32 v4, v4
	v_pk_mul_f32 v[6:7], v[0:1], v[6:7] op_sel_hi:[0,1]
	v_lshlrev_b32_e32 v8, 16, v21
	v_add_f32_e32 v4, 1.0, v4
	v_rcp_f32_e32 v28, v4
	v_mul_f32_e32 v4, 0xbfb8aa3b, v27
	v_exp_f32_e32 v4, v4
	s_nop 0
	v_add_f32_e32 v4, 1.0, v4
	v_rcp_f32_e32 v29, v4
	s_nop 0
	v_pk_mul_f32 v[26:27], v[28:29], v[26:27]
	s_nop 0
	v_pk_mul_f32 v[6:7], v[26:27], v[6:7]
	s_nop 0
	v_cvt_pk_bf16_f32 v4, v6, v7
	v_lshlrev_b32_e32 v6, 16, v9
	v_and_b32_e32 v7, 0xffff0000, v9
	v_and_b32_e32 v9, 0xffff0000, v21
	v_pk_mul_f32 v[8:9], v[22:23], v[8:9] op_sel_hi:[0,1]
	v_pk_fma_f32 v[6:7], v[24:25], v[6:7], v[8:9] op_sel_hi:[0,1,1]
	v_lshlrev_b32_e32 v8, 16, v19
	v_and_b32_e32 v9, 0xffff0000, v19
	v_pk_fma_f32 v[6:7], v[18:19], v[8:9], v[6:7] op_sel_hi:[0,1,1]
	v_lshlrev_b32_e32 v8, 16, v15
	v_and_b32_e32 v9, 0xffff0000, v15
	v_pk_fma_f32 v[6:7], v[20:21], v[8:9], v[6:7] op_sel_hi:[0,1,1]
	v_lshlrev_b32_e32 v8, 16, v5
	v_and_b32_e32 v9, 0xffff0000, v5
	v_mul_f32_e32 v5, 0xbfb8aa3b, v8
	v_pk_mul_f32 v[6:7], v[0:1], v[6:7] op_sel_hi:[0,1]
	v_mul_f32_e32 v0, 0xbfb8aa3b, v9
	v_exp_f32_e32 v5, v5
	v_exp_f32_e32 v0, v0
	v_add_f32_e32 v5, 1.0, v5
	v_add_f32_e32 v0, 1.0, v0
	v_rcp_f32_e32 v18, v5
	v_rcp_f32_e32 v19, v0
	s_nop 0
	v_pk_mul_f32 v[8:9], v[18:19], v[8:9]
	s_nop 0
	v_pk_mul_f32 v[6:7], v[8:9], v[6:7]
	s_nop 0
	v_cvt_pk_bf16_f32 v5, v6, v7
	global_store_dwordx4 v[16:17], v[2:5], off
	s_branch .LBB0_582
	s_nop 0
	s_nop 0
	s_nop 0
	s_nop 0
	s_nop 0
	s_nop 0
	s_nop 0
	s_nop 0
	s_nop 0
	s_nop 0
	s_nop 0
	s_nop 0
	s_nop 0
	s_nop 0
	s_nop 0
	s_nop 0
	s_nop 0
	s_nop 0
	s_nop 0
	s_nop 0
	s_nop 0
	s_nop 0
	s_nop 0
	s_nop 0
	s_nop 0
	s_nop 0
	s_nop 0
	s_nop 0
	s_nop 0
	s_nop 0
	s_nop 0
	s_nop 0
